# diff-attn: software-pipelined no-mask tile fast path (LDS prefetch ring, 2 S tiles)
# speedup vs baseline: 1.0492x; 1.0492x over previous
.Ldiff_fast0:
	s_lshl_b32 s1, s0, 16
	v_add3_u32 v14, s1, v215, v216
	v_add3_u32 v15, s1, v195, v224
	ds_read_b128 v[2:5], v14
	v_xor_b32_e32 v217, 32, v14
	ds_read_b128 v[6:9], v217
	v_xor_b32_e32 v222, 64, v14
	ds_read_b128 v[10:13], v222
	v_xor_b32_e32 v217, 0x60, v14
	ds_read_b128 v[218:221], v217
	s_waitcnt lgkmcnt(3)
	v_mfma_f32_32x32x16_bf16 v[144:159], v[2:5], v[160:163], 0
	v_xor_b32_e32 v222, 0x80, v14
	ds_read_b128 v[226:229], v222
	s_waitcnt lgkmcnt(3)
	v_mfma_f32_32x32x16_bf16 v[144:159], v[6:9], v[164:167], v[144:159]
	v_xor_b32_e32 v217, 0xa0, v14
	ds_read_b128 v[2:5], v217
	s_waitcnt lgkmcnt(3)
	v_mfma_f32_32x32x16_bf16 v[144:159], v[10:13], v[168:171], v[144:159]
	v_xor_b32_e32 v222, 0xc0, v14
	ds_read_b128 v[6:9], v222
	s_waitcnt lgkmcnt(3)
	v_mfma_f32_32x32x16_bf16 v[144:159], v[218:221], v[172:175], v[144:159]
	v_xor_b32_e32 v217, 0xe0, v14
	ds_read_b128 v[10:13], v217
	s_waitcnt lgkmcnt(3)
	v_mfma_f32_32x32x16_bf16 v[236:251], v[226:229], v[176:179], 0
	ds_read_b128 v[218:221], v15 offset:32768
	s_waitcnt lgkmcnt(3)
	v_mfma_f32_32x32x16_bf16 v[236:251], v[2:5], v[180:183], v[236:251]
	ds_read_b128 v[226:229], v15 offset:40960
	s_nop 3
	v_exp_f32_e32 v144, v144
	v_exp_f32_e32 v145, v145
	v_exp_f32_e32 v146, v146
	v_add_f32_e32 v0, v144, v145
	s_waitcnt lgkmcnt(3)
	v_mfma_f32_32x32x16_bf16 v[236:251], v[6:9], v[184:187], v[236:251]
	ds_read_b128 v[2:5], v15 offset:49152
	v_exp_f32_e32 v147, v147
	v_add_f32_e32 v0, v146, v0
	v_cvt_pk_bf16_f32 v144, v144, v145
	v_exp_f32_e32 v148, v148
	s_waitcnt lgkmcnt(3)
	v_mfma_f32_32x32x16_bf16 v[236:251], v[10:13], v[188:191], v[236:251]
	ds_read_b128 v[6:9], v15 offset:57344
	v_add_f32_e32 v0, v147, v0
	v_cvt_pk_bf16_f32 v145, v146, v147
	v_exp_f32_e32 v149, v149
	v_add_f32_e32 v0, v148, v0
	v_exp_f32_e32 v150, v150
	v_add_f32_e32 v0, v149, v0
	v_cvt_pk_bf16_f32 v146, v148, v149
	v_exp_f32_e32 v151, v151
	v_add_f32_e32 v0, v150, v0
	v_exp_f32_e32 v152, v152
	v_add_f32_e32 v0, v151, v0
	v_cvt_pk_bf16_f32 v147, v150, v151
	s_waitcnt lgkmcnt(3)
	s_nop 0
	v_mfma_f32_32x32x16_bf16 v[128:143], v[218:221], v[144:147], v[128:143]
	v_xor_b32_e32 v223, 32, v15
	ds_read_b128 v[10:13], v223 offset:32768
	v_exp_f32_e32 v153, v153
	v_add_f32_e32 v0, v152, v0
	v_exp_f32_e32 v154, v154
	v_add_f32_e32 v0, v153, v0
	s_waitcnt lgkmcnt(3)
	v_mfma_f32_32x32x16_bf16 v[112:127], v[226:229], v[144:147], v[112:127]
	ds_read_b128 v[218:221], v223 offset:40960
	v_cvt_pk_bf16_f32 v148, v152, v153
	v_exp_f32_e32 v155, v155
	v_add_f32_e32 v0, v154, v0
	v_exp_f32_e32 v156, v156
	s_waitcnt lgkmcnt(3)
	v_mfma_f32_32x32x16_bf16 v[96:111], v[2:5], v[144:147], v[96:111]
	ds_read_b128 v[226:229], v223 offset:49152
	v_add_f32_e32 v0, v155, v0
	v_cvt_pk_bf16_f32 v149, v154, v155
	v_exp_f32_e32 v157, v157
	v_add_f32_e32 v0, v156, v0
	s_waitcnt lgkmcnt(3)
	v_mfma_f32_32x32x16_bf16 v[80:95], v[6:9], v[144:147], v[80:95]
	ds_read_b128 v[2:5], v223 offset:57344
	v_exp_f32_e32 v158, v158
	v_add_f32_e32 v0, v157, v0
	v_cvt_pk_bf16_f32 v150, v156, v157
	v_exp_f32_e32 v159, v159
	v_add_f32_e32 v0, v158, v0
	v_add_f32_e32 v0, v159, v0
	v_cvt_pk_bf16_f32 v151, v158, v159
	s_waitcnt lgkmcnt(3)
	s_nop 0
	v_mfma_f32_32x32x16_bf16 v[128:143], v[10:13], v[148:151], v[128:143]
	ds_read_b128 v[6:9], v14 offset:8192
	v_add_f32_e32 v197, v197, v0
	v_exp_f32_e32 v236, v236
	v_exp_f32_e32 v237, v237
	v_exp_f32_e32 v238, v238
	s_waitcnt lgkmcnt(3)
	v_mfma_f32_32x32x16_bf16 v[112:127], v[218:221], v[148:151], v[112:127]
	v_xor_b32_e32 v222, 32, v14
	ds_read_b128 v[10:13], v222 offset:8192
	v_add_f32_e32 v0, v236, v237
	v_exp_f32_e32 v239, v239
	v_add_f32_e32 v0, v238, v0
	v_cvt_pk_bf16_f32 v236, v236, v237
	s_waitcnt lgkmcnt(3)
	v_mfma_f32_32x32x16_bf16 v[96:111], v[226:229], v[148:151], v[96:111]
	v_xor_b32_e32 v217, 64, v14
	ds_read_b128 v[218:221], v217 offset:8192
	v_exp_f32_e32 v240, v240
	v_add_f32_e32 v0, v239, v0
	v_cvt_pk_bf16_f32 v237, v238, v239
	v_exp_f32_e32 v241, v241
	s_waitcnt lgkmcnt(3)
	v_mfma_f32_32x32x16_bf16 v[80:95], v[2:5], v[148:151], v[80:95]
	v_xor_b32_e32 v222, 0x60, v14
	ds_read_b128 v[226:229], v222 offset:8192
	v_add_f32_e32 v0, v240, v0
	v_exp_f32_e32 v242, v242
	v_add_f32_e32 v0, v241, v0
	v_cvt_pk_bf16_f32 v238, v240, v241
	s_waitcnt lgkmcnt(3)
	v_mfma_f32_32x32x16_bf16 v[144:159], v[6:9], v[160:163], 0
	ds_read_b128 v[2:5], v15 offset:32768
	v_exp_f32_e32 v243, v243
	v_add_f32_e32 v0, v242, v0
	v_exp_f32_e32 v244, v244
	v_add_f32_e32 v0, v243, v0
	s_waitcnt lgkmcnt(3)
	v_mfma_f32_32x32x16_bf16 v[144:159], v[10:13], v[164:167], v[144:159]
	ds_read_b128 v[6:9], v15 offset:40960
	v_cvt_pk_bf16_f32 v239, v242, v243
	v_exp_f32_e32 v245, v245
	v_add_f32_e32 v0, v244, v0
	v_exp_f32_e32 v246, v246
	s_waitcnt lgkmcnt(3)
	v_mfma_f32_32x32x16_bf16 v[144:159], v[218:221], v[168:171], v[144:159]
	ds_read_b128 v[10:13], v15 offset:49152
	v_add_f32_e32 v0, v245, v0
	v_cvt_pk_bf16_f32 v240, v244, v245
	v_exp_f32_e32 v247, v247
	v_add_f32_e32 v0, v246, v0
	s_waitcnt lgkmcnt(3)
	v_mfma_f32_32x32x16_bf16 v[144:159], v[226:229], v[172:175], v[144:159]
	ds_read_b128 v[218:221], v15 offset:57344
	v_exp_f32_e32 v248, v248
	v_add_f32_e32 v0, v247, v0
	v_cvt_pk_bf16_f32 v241, v246, v247
	v_exp_f32_e32 v249, v249
	s_waitcnt lgkmcnt(3)
	v_mfma_f32_32x32x16_bf16 v[64:79], v[2:5], v[236:239], v[64:79]
	v_xor_b32_e32 v225, 32, v15
	ds_read_b128 v[226:229], v225 offset:32768
	v_add_f32_e32 v0, v248, v0
	v_exp_f32_e32 v250, v250
	v_add_f32_e32 v0, v249, v0
	v_cvt_pk_bf16_f32 v242, v248, v249
	s_waitcnt lgkmcnt(3)
	v_mfma_f32_32x32x16_bf16 v[48:63], v[6:9], v[236:239], v[48:63]
	ds_read_b128 v[2:5], v225 offset:40960
	v_exp_f32_e32 v251, v251
	v_add_f32_e32 v0, v250, v0
	v_add_f32_e32 v0, v251, v0
	v_cvt_pk_bf16_f32 v243, v250, v251
	s_waitcnt lgkmcnt(3)
	v_mfma_f32_32x32x16_bf16 v[32:47], v[10:13], v[236:239], v[32:47]
	ds_read_b128 v[6:9], v225 offset:49152
	v_add_f32_e32 v196, v196, v0
	v_exp_f32_e32 v144, v144
	v_exp_f32_e32 v145, v145
	v_exp_f32_e32 v146, v146
	s_waitcnt lgkmcnt(3)
	v_mfma_f32_32x32x16_bf16 v[16:31], v[218:221], v[236:239], v[16:31]
	ds_read_b128 v[10:13], v225 offset:57344
	v_add_f32_e32 v0, v144, v145
	v_exp_f32_e32 v147, v147
	v_add_f32_e32 v0, v146, v0
	v_cvt_pk_bf16_f32 v144, v144, v145
	s_waitcnt lgkmcnt(3)
	v_mfma_f32_32x32x16_bf16 v[64:79], v[226:229], v[240:243], v[64:79]
	v_xor_b32_e32 v217, 0x80, v14
	ds_read_b128 v[218:221], v217 offset:8192
	v_exp_f32_e32 v148, v148
	v_add_f32_e32 v0, v147, v0
	v_cvt_pk_bf16_f32 v145, v146, v147
	v_exp_f32_e32 v149, v149
	s_waitcnt lgkmcnt(3)
	v_mfma_f32_32x32x16_bf16 v[48:63], v[2:5], v[240:243], v[48:63]
	v_xor_b32_e32 v222, 0xa0, v14
	ds_read_b128 v[226:229], v222 offset:8192
	v_add_f32_e32 v0, v148, v0
	v_exp_f32_e32 v150, v150
	v_add_f32_e32 v0, v149, v0
	v_cvt_pk_bf16_f32 v146, v148, v149
	s_waitcnt lgkmcnt(3)
	v_mfma_f32_32x32x16_bf16 v[32:47], v[6:9], v[240:243], v[32:47]
	v_xor_b32_e32 v217, 0xc0, v14
	ds_read_b128 v[2:5], v217 offset:8192
	v_exp_f32_e32 v151, v151
	v_add_f32_e32 v0, v150, v0
	v_exp_f32_e32 v152, v152
	v_add_f32_e32 v0, v151, v0
	s_waitcnt lgkmcnt(3)
	v_mfma_f32_32x32x16_bf16 v[16:31], v[10:13], v[240:243], v[16:31]
	v_xor_b32_e32 v222, 0xe0, v14
	ds_read_b128 v[6:9], v222 offset:8192
	v_cvt_pk_bf16_f32 v147, v150, v151
	v_exp_f32_e32 v153, v153
	v_add_f32_e32 v0, v152, v0
	v_exp_f32_e32 v154, v154
	s_waitcnt lgkmcnt(3)
	v_mfma_f32_32x32x16_bf16 v[236:251], v[218:221], v[176:179], 0
	v_xor_b32_e32 v223, 64, v15
	ds_read_b128 v[10:13], v223 offset:32768
	v_add_f32_e32 v0, v153, v0
	v_cvt_pk_bf16_f32 v148, v152, v153
	v_exp_f32_e32 v155, v155
	v_add_f32_e32 v0, v154, v0
	s_waitcnt lgkmcnt(3)
	v_mfma_f32_32x32x16_bf16 v[236:251], v[226:229], v[180:183], v[236:251]
	ds_read_b128 v[218:221], v223 offset:40960
	v_exp_f32_e32 v156, v156
	v_add_f32_e32 v0, v155, v0
	v_cvt_pk_bf16_f32 v149, v154, v155
	v_exp_f32_e32 v157, v157
	s_waitcnt lgkmcnt(3)
	v_mfma_f32_32x32x16_bf16 v[236:251], v[2:5], v[184:187], v[236:251]
	ds_read_b128 v[226:229], v223 offset:49152
	v_add_f32_e32 v0, v156, v0
	v_exp_f32_e32 v158, v158
	v_add_f32_e32 v0, v157, v0
	v_cvt_pk_bf16_f32 v150, v156, v157
	s_waitcnt lgkmcnt(3)
	v_mfma_f32_32x32x16_bf16 v[236:251], v[6:9], v[188:191], v[236:251]
	ds_read_b128 v[2:5], v223 offset:57344
	v_exp_f32_e32 v159, v159
	v_add_f32_e32 v0, v158, v0
	v_add_f32_e32 v0, v159, v0
	v_cvt_pk_bf16_f32 v151, v158, v159
	s_waitcnt lgkmcnt(3)
	v_mfma_f32_32x32x16_bf16 v[128:143], v[10:13], v[144:147], v[128:143]
	v_xor_b32_e32 v225, 0x60, v15
	ds_read_b128 v[6:9], v225 offset:32768
	v_add_f32_e32 v197, v197, v0
	s_waitcnt lgkmcnt(3)
	v_mfma_f32_32x32x16_bf16 v[112:127], v[218:221], v[144:147], v[112:127]
	ds_read_b128 v[10:13], v225 offset:40960
	v_exp_f32_e32 v236, v236
	v_exp_f32_e32 v237, v237
	v_exp_f32_e32 v238, v238
	v_add_f32_e32 v0, v236, v237
	s_waitcnt lgkmcnt(3)
	v_mfma_f32_32x32x16_bf16 v[96:111], v[226:229], v[144:147], v[96:111]
	ds_read_b128 v[218:221], v225 offset:49152
	v_exp_f32_e32 v239, v239
	v_add_f32_e32 v0, v238, v0
	v_cvt_pk_bf16_f32 v236, v236, v237
	v_exp_f32_e32 v240, v240
	s_waitcnt lgkmcnt(3)
	v_mfma_f32_32x32x16_bf16 v[80:95], v[2:5], v[144:147], v[80:95]
	ds_read_b128 v[226:229], v225 offset:57344
	v_add_f32_e32 v0, v239, v0
	v_cvt_pk_bf16_f32 v237, v238, v239
	v_exp_f32_e32 v241, v241
	v_add_f32_e32 v0, v240, v0
	s_waitcnt lgkmcnt(3)
	v_mfma_f32_32x32x16_bf16 v[128:143], v[6:9], v[148:151], v[128:143]
	ds_read_b128 v[2:5], v14 offset:16384
	v_exp_f32_e32 v242, v242
	v_add_f32_e32 v0, v241, v0
	v_cvt_pk_bf16_f32 v238, v240, v241
	v_exp_f32_e32 v243, v243
	s_waitcnt lgkmcnt(3)
	v_mfma_f32_32x32x16_bf16 v[112:127], v[10:13], v[148:151], v[112:127]
	v_xor_b32_e32 v217, 32, v14
	ds_read_b128 v[6:9], v217 offset:16384
	v_add_f32_e32 v0, v242, v0
	v_exp_f32_e32 v244, v244
	v_add_f32_e32 v0, v243, v0
	v_cvt_pk_bf16_f32 v239, v242, v243
	s_waitcnt lgkmcnt(3)
	v_mfma_f32_32x32x16_bf16 v[96:111], v[218:221], v[148:151], v[96:111]
	v_xor_b32_e32 v222, 64, v14
	ds_read_b128 v[10:13], v222 offset:16384
	v_exp_f32_e32 v245, v245
	v_add_f32_e32 v0, v244, v0
	v_exp_f32_e32 v246, v246
	v_add_f32_e32 v0, v245, v0
	s_waitcnt lgkmcnt(3)
	v_mfma_f32_32x32x16_bf16 v[80:95], v[226:229], v[148:151], v[80:95]
	v_xor_b32_e32 v217, 0x60, v14
	ds_read_b128 v[218:221], v217 offset:16384
	v_cvt_pk_bf16_f32 v240, v244, v245
	v_exp_f32_e32 v247, v247
	v_add_f32_e32 v0, v246, v0
	v_exp_f32_e32 v248, v248
	s_waitcnt lgkmcnt(3)
	v_mfma_f32_32x32x16_bf16 v[144:159], v[2:5], v[160:163], 0
	v_xor_b32_e32 v223, 64, v15
	ds_read_b128 v[226:229], v223 offset:32768
	v_add_f32_e32 v0, v247, v0
	v_cvt_pk_bf16_f32 v241, v246, v247
	v_exp_f32_e32 v249, v249
	v_add_f32_e32 v0, v248, v0
	s_waitcnt lgkmcnt(3)
	v_mfma_f32_32x32x16_bf16 v[144:159], v[6:9], v[164:167], v[144:159]
	ds_read_b128 v[2:5], v223 offset:40960
	v_exp_f32_e32 v250, v250
	v_add_f32_e32 v0, v249, v0
	v_cvt_pk_bf16_f32 v242, v248, v249
	v_exp_f32_e32 v251, v251
	s_waitcnt lgkmcnt(3)
	v_mfma_f32_32x32x16_bf16 v[144:159], v[10:13], v[168:171], v[144:159]
	ds_read_b128 v[6:9], v223 offset:49152
	v_add_f32_e32 v0, v250, v0
	v_add_f32_e32 v0, v251, v0
	v_cvt_pk_bf16_f32 v243, v250, v251
	v_add_f32_e32 v196, v196, v0
	s_waitcnt lgkmcnt(3)
	v_mfma_f32_32x32x16_bf16 v[144:159], v[218:221], v[172:175], v[144:159]
	ds_read_b128 v[10:13], v223 offset:57344
	s_waitcnt lgkmcnt(3)
	v_mfma_f32_32x32x16_bf16 v[64:79], v[226:229], v[236:239], v[64:79]
	v_xor_b32_e32 v225, 0x60, v15
	ds_read_b128 v[218:221], v225 offset:32768
	s_waitcnt lgkmcnt(3)
	v_mfma_f32_32x32x16_bf16 v[48:63], v[2:5], v[236:239], v[48:63]
	ds_read_b128 v[226:229], v225 offset:40960
	s_nop 3
	v_exp_f32_e32 v144, v144
	v_exp_f32_e32 v145, v145
	v_exp_f32_e32 v146, v146
	v_add_f32_e32 v0, v144, v145
	s_waitcnt lgkmcnt(3)
	v_mfma_f32_32x32x16_bf16 v[32:47], v[6:9], v[236:239], v[32:47]
	ds_read_b128 v[2:5], v225 offset:49152
	v_exp_f32_e32 v147, v147
	v_add_f32_e32 v0, v146, v0
	v_cvt_pk_bf16_f32 v144, v144, v145
	v_exp_f32_e32 v148, v148
	s_waitcnt lgkmcnt(3)
	v_mfma_f32_32x32x16_bf16 v[16:31], v[10:13], v[236:239], v[16:31]
	ds_read_b128 v[6:9], v225 offset:57344
	v_add_f32_e32 v0, v147, v0
	v_cvt_pk_bf16_f32 v145, v146, v147
	v_exp_f32_e32 v149, v149
	v_add_f32_e32 v0, v148, v0
	s_waitcnt lgkmcnt(3)
	v_mfma_f32_32x32x16_bf16 v[64:79], v[218:221], v[240:243], v[64:79]
	v_xor_b32_e32 v222, 0x80, v14
	ds_read_b128 v[10:13], v222 offset:16384
	v_exp_f32_e32 v150, v150
	v_add_f32_e32 v0, v149, v0
	v_cvt_pk_bf16_f32 v146, v148, v149
	v_exp_f32_e32 v151, v151
	s_waitcnt lgkmcnt(3)
	v_mfma_f32_32x32x16_bf16 v[48:63], v[226:229], v[240:243], v[48:63]
	v_xor_b32_e32 v217, 0xa0, v14
	ds_read_b128 v[218:221], v217 offset:16384
	v_add_f32_e32 v0, v150, v0
	v_exp_f32_e32 v152, v152
	v_add_f32_e32 v0, v151, v0
	v_cvt_pk_bf16_f32 v147, v150, v151
	s_waitcnt lgkmcnt(3)
	v_mfma_f32_32x32x16_bf16 v[32:47], v[2:5], v[240:243], v[32:47]
	v_xor_b32_e32 v222, 0xc0, v14
	ds_read_b128 v[226:229], v222 offset:16384
	v_exp_f32_e32 v153, v153
	v_add_f32_e32 v0, v152, v0
	v_exp_f32_e32 v154, v154
	v_add_f32_e32 v0, v153, v0
	s_waitcnt lgkmcnt(3)
	v_mfma_f32_32x32x16_bf16 v[16:31], v[6:9], v[240:243], v[16:31]
	v_xor_b32_e32 v217, 0xe0, v14
	ds_read_b128 v[2:5], v217 offset:16384
	v_cvt_pk_bf16_f32 v148, v152, v153
	v_exp_f32_e32 v155, v155
	v_add_f32_e32 v0, v154, v0
	v_exp_f32_e32 v156, v156
	s_waitcnt lgkmcnt(3)
	v_mfma_f32_32x32x16_bf16 v[236:251], v[10:13], v[176:179], 0
	v_xor_b32_e32 v223, 0x80, v15
	ds_read_b128 v[6:9], v223 offset:32768
	v_add_f32_e32 v0, v155, v0
	v_cvt_pk_bf16_f32 v149, v154, v155
	v_exp_f32_e32 v157, v157
	v_add_f32_e32 v0, v156, v0
	s_waitcnt lgkmcnt(3)
	v_mfma_f32_32x32x16_bf16 v[236:251], v[218:221], v[180:183], v[236:251]
	ds_read_b128 v[10:13], v223 offset:40960
	v_exp_f32_e32 v158, v158
	v_add_f32_e32 v0, v157, v0
	v_cvt_pk_bf16_f32 v150, v156, v157
	v_exp_f32_e32 v159, v159
	s_waitcnt lgkmcnt(3)
	v_mfma_f32_32x32x16_bf16 v[236:251], v[226:229], v[184:187], v[236:251]
	ds_read_b128 v[218:221], v223 offset:49152
	v_add_f32_e32 v0, v158, v0
	v_add_f32_e32 v0, v159, v0
	v_cvt_pk_bf16_f32 v151, v158, v159
	v_add_f32_e32 v197, v197, v0
	s_waitcnt lgkmcnt(3)
	v_mfma_f32_32x32x16_bf16 v[236:251], v[2:5], v[188:191], v[236:251]
	ds_read_b128 v[226:229], v223 offset:57344
	s_waitcnt lgkmcnt(3)
	v_mfma_f32_32x32x16_bf16 v[128:143], v[6:9], v[144:147], v[128:143]
	v_xor_b32_e32 v225, 0xa0, v15
	ds_read_b128 v[2:5], v225 offset:32768
	s_waitcnt lgkmcnt(3)
	v_mfma_f32_32x32x16_bf16 v[112:127], v[10:13], v[144:147], v[112:127]
	ds_read_b128 v[6:9], v225 offset:40960
	s_nop 3
	v_exp_f32_e32 v236, v236
	v_exp_f32_e32 v237, v237
	v_exp_f32_e32 v238, v238
	v_add_f32_e32 v0, v236, v237
	s_waitcnt lgkmcnt(3)
	v_mfma_f32_32x32x16_bf16 v[96:111], v[218:221], v[144:147], v[96:111]
	ds_read_b128 v[10:13], v225 offset:49152
	v_exp_f32_e32 v239, v239
	v_add_f32_e32 v0, v238, v0
	v_cvt_pk_bf16_f32 v236, v236, v237
	v_exp_f32_e32 v240, v240
	s_waitcnt lgkmcnt(3)
	v_mfma_f32_32x32x16_bf16 v[80:95], v[226:229], v[144:147], v[80:95]
	ds_read_b128 v[218:221], v225 offset:57344
	v_add_f32_e32 v0, v239, v0
	v_cvt_pk_bf16_f32 v237, v238, v239
	v_exp_f32_e32 v241, v241
	v_add_f32_e32 v0, v240, v0
	s_waitcnt lgkmcnt(3)
	v_mfma_f32_32x32x16_bf16 v[128:143], v[2:5], v[148:151], v[128:143]
	ds_read_b128 v[226:229], v14 offset:24576
	v_exp_f32_e32 v242, v242
	v_add_f32_e32 v0, v241, v0
	v_cvt_pk_bf16_f32 v238, v240, v241
	v_exp_f32_e32 v243, v243
	s_waitcnt lgkmcnt(3)
	v_mfma_f32_32x32x16_bf16 v[112:127], v[6:9], v[148:151], v[112:127]
	v_xor_b32_e32 v222, 32, v14
	ds_read_b128 v[2:5], v222 offset:24576
	v_add_f32_e32 v0, v242, v0
	v_exp_f32_e32 v244, v244
	v_add_f32_e32 v0, v243, v0
	v_cvt_pk_bf16_f32 v239, v242, v243
	s_waitcnt lgkmcnt(3)
	v_mfma_f32_32x32x16_bf16 v[96:111], v[10:13], v[148:151], v[96:111]
	v_xor_b32_e32 v217, 64, v14
	ds_read_b128 v[6:9], v217 offset:24576
	v_exp_f32_e32 v245, v245
	v_add_f32_e32 v0, v244, v0
	v_exp_f32_e32 v246, v246
	v_add_f32_e32 v0, v245, v0
	s_waitcnt lgkmcnt(3)
	v_mfma_f32_32x32x16_bf16 v[80:95], v[218:221], v[148:151], v[80:95]
	v_xor_b32_e32 v222, 0x60, v14
	ds_read_b128 v[10:13], v222 offset:24576
	v_cvt_pk_bf16_f32 v240, v244, v245
	v_exp_f32_e32 v247, v247
	v_add_f32_e32 v0, v246, v0
	v_exp_f32_e32 v248, v248
	s_waitcnt lgkmcnt(3)
	v_mfma_f32_32x32x16_bf16 v[144:159], v[226:229], v[160:163], 0
	v_xor_b32_e32 v223, 0x80, v15
	ds_read_b128 v[218:221], v223 offset:32768
	v_add_f32_e32 v0, v247, v0
	v_cvt_pk_bf16_f32 v241, v246, v247
	v_exp_f32_e32 v249, v249
	v_add_f32_e32 v0, v248, v0
	s_waitcnt lgkmcnt(3)
	v_mfma_f32_32x32x16_bf16 v[144:159], v[2:5], v[164:167], v[144:159]
	ds_read_b128 v[226:229], v223 offset:40960
	v_exp_f32_e32 v250, v250
	v_add_f32_e32 v0, v249, v0
	v_cvt_pk_bf16_f32 v242, v248, v249
	v_exp_f32_e32 v251, v251
	s_waitcnt lgkmcnt(3)
	v_mfma_f32_32x32x16_bf16 v[144:159], v[6:9], v[168:171], v[144:159]
	ds_read_b128 v[2:5], v223 offset:49152
	v_add_f32_e32 v0, v250, v0
	v_add_f32_e32 v0, v251, v0
	v_cvt_pk_bf16_f32 v243, v250, v251
	v_add_f32_e32 v196, v196, v0
	s_waitcnt lgkmcnt(3)
	v_mfma_f32_32x32x16_bf16 v[144:159], v[10:13], v[172:175], v[144:159]
	ds_read_b128 v[6:9], v223 offset:57344
	s_waitcnt lgkmcnt(3)
	v_mfma_f32_32x32x16_bf16 v[64:79], v[218:221], v[236:239], v[64:79]
	v_xor_b32_e32 v225, 0xa0, v15
	ds_read_b128 v[10:13], v225 offset:32768
	s_waitcnt lgkmcnt(3)
	v_mfma_f32_32x32x16_bf16 v[48:63], v[226:229], v[236:239], v[48:63]
	ds_read_b128 v[218:221], v225 offset:40960
	s_nop 3
	v_exp_f32_e32 v144, v144
	v_exp_f32_e32 v145, v145
	v_exp_f32_e32 v146, v146
	v_add_f32_e32 v0, v144, v145
	s_waitcnt lgkmcnt(3)
	v_mfma_f32_32x32x16_bf16 v[32:47], v[2:5], v[236:239], v[32:47]
	ds_read_b128 v[226:229], v225 offset:49152
	v_exp_f32_e32 v147, v147
	v_add_f32_e32 v0, v146, v0
	v_cvt_pk_bf16_f32 v144, v144, v145
	v_exp_f32_e32 v148, v148
	s_waitcnt lgkmcnt(3)
	v_mfma_f32_32x32x16_bf16 v[16:31], v[6:9], v[236:239], v[16:31]
	ds_read_b128 v[2:5], v225 offset:57344
	v_add_f32_e32 v0, v147, v0
	v_cvt_pk_bf16_f32 v145, v146, v147
	v_exp_f32_e32 v149, v149
	v_add_f32_e32 v0, v148, v0
	s_waitcnt lgkmcnt(3)
	v_mfma_f32_32x32x16_bf16 v[64:79], v[10:13], v[240:243], v[64:79]
	v_xor_b32_e32 v217, 0x80, v14
	ds_read_b128 v[6:9], v217 offset:24576
	v_exp_f32_e32 v150, v150
	v_add_f32_e32 v0, v149, v0
	v_cvt_pk_bf16_f32 v146, v148, v149
	v_exp_f32_e32 v151, v151
	s_waitcnt lgkmcnt(3)
	v_mfma_f32_32x32x16_bf16 v[48:63], v[218:221], v[240:243], v[48:63]
	v_xor_b32_e32 v222, 0xa0, v14
	ds_read_b128 v[10:13], v222 offset:24576
	v_add_f32_e32 v0, v150, v0
	v_exp_f32_e32 v152, v152
	v_add_f32_e32 v0, v151, v0
	v_cvt_pk_bf16_f32 v147, v150, v151
	s_waitcnt lgkmcnt(3)
	v_mfma_f32_32x32x16_bf16 v[32:47], v[226:229], v[240:243], v[32:47]
	v_xor_b32_e32 v217, 0xc0, v14
	ds_read_b128 v[218:221], v217 offset:24576
	v_exp_f32_e32 v153, v153
	v_add_f32_e32 v0, v152, v0
	v_exp_f32_e32 v154, v154
	v_add_f32_e32 v0, v153, v0
	s_waitcnt lgkmcnt(3)
	v_mfma_f32_32x32x16_bf16 v[16:31], v[2:5], v[240:243], v[16:31]
	v_xor_b32_e32 v222, 0xe0, v14
	ds_read_b128 v[226:229], v222 offset:24576
	v_cvt_pk_bf16_f32 v148, v152, v153
	v_exp_f32_e32 v155, v155
	v_add_f32_e32 v0, v154, v0
	v_exp_f32_e32 v156, v156
	s_waitcnt lgkmcnt(3)
	v_mfma_f32_32x32x16_bf16 v[236:251], v[6:9], v[176:179], 0
	v_xor_b32_e32 v223, 0xc0, v15
	ds_read_b128 v[2:5], v223 offset:32768
	v_add_f32_e32 v0, v155, v0
	v_cvt_pk_bf16_f32 v149, v154, v155
	v_exp_f32_e32 v157, v157
	v_add_f32_e32 v0, v156, v0
	s_waitcnt lgkmcnt(3)
	v_mfma_f32_32x32x16_bf16 v[236:251], v[10:13], v[180:183], v[236:251]
	ds_read_b128 v[6:9], v223 offset:40960
	v_exp_f32_e32 v158, v158
	v_add_f32_e32 v0, v157, v0
	v_cvt_pk_bf16_f32 v150, v156, v157
	v_exp_f32_e32 v159, v159
	s_waitcnt lgkmcnt(3)
	v_mfma_f32_32x32x16_bf16 v[236:251], v[218:221], v[184:187], v[236:251]
	ds_read_b128 v[10:13], v223 offset:49152
	v_add_f32_e32 v0, v158, v0
	v_add_f32_e32 v0, v159, v0
	v_cvt_pk_bf16_f32 v151, v158, v159
	v_add_f32_e32 v197, v197, v0
	s_waitcnt lgkmcnt(3)
	v_mfma_f32_32x32x16_bf16 v[236:251], v[226:229], v[188:191], v[236:251]
	ds_read_b128 v[218:221], v223 offset:57344
	s_waitcnt lgkmcnt(3)
	v_mfma_f32_32x32x16_bf16 v[128:143], v[2:5], v[144:147], v[128:143]
	v_xor_b32_e32 v225, 0xe0, v15
	ds_read_b128 v[226:229], v225 offset:32768
	s_waitcnt lgkmcnt(3)
	v_mfma_f32_32x32x16_bf16 v[112:127], v[6:9], v[144:147], v[112:127]
	ds_read_b128 v[2:5], v225 offset:40960
	s_nop 3
	v_exp_f32_e32 v236, v236
	v_exp_f32_e32 v237, v237
	v_exp_f32_e32 v238, v238
	v_add_f32_e32 v0, v236, v237
	s_waitcnt lgkmcnt(3)
	v_mfma_f32_32x32x16_bf16 v[96:111], v[10:13], v[144:147], v[96:111]
	ds_read_b128 v[6:9], v225 offset:49152
	v_exp_f32_e32 v239, v239
	v_add_f32_e32 v0, v238, v0
	v_cvt_pk_bf16_f32 v236, v236, v237
	v_exp_f32_e32 v240, v240
	s_waitcnt lgkmcnt(3)
	v_mfma_f32_32x32x16_bf16 v[80:95], v[218:221], v[144:147], v[80:95]
	ds_read_b128 v[10:13], v225 offset:57344
	v_add_f32_e32 v0, v239, v0
	v_cvt_pk_bf16_f32 v237, v238, v239
	v_exp_f32_e32 v241, v241
	v_add_f32_e32 v0, v240, v0
	s_waitcnt lgkmcnt(3)
	v_mfma_f32_32x32x16_bf16 v[128:143], v[226:229], v[148:151], v[128:143]
	v_xor_b32_e32 v223, 0xc0, v15
	ds_read_b128 v[218:221], v223 offset:32768
	v_exp_f32_e32 v242, v242
	v_add_f32_e32 v0, v241, v0
	v_cvt_pk_bf16_f32 v238, v240, v241
	v_exp_f32_e32 v243, v243
	s_waitcnt lgkmcnt(3)
	v_mfma_f32_32x32x16_bf16 v[112:127], v[2:5], v[148:151], v[112:127]
	ds_read_b128 v[226:229], v223 offset:40960
	v_add_f32_e32 v0, v242, v0
	v_exp_f32_e32 v244, v244
	v_add_f32_e32 v0, v243, v0
	v_cvt_pk_bf16_f32 v239, v242, v243
	s_waitcnt lgkmcnt(3)
	v_mfma_f32_32x32x16_bf16 v[96:111], v[6:9], v[148:151], v[96:111]
	ds_read_b128 v[2:5], v223 offset:49152
	v_exp_f32_e32 v245, v245
	v_add_f32_e32 v0, v244, v0
	v_exp_f32_e32 v246, v246
	v_add_f32_e32 v0, v245, v0
	s_waitcnt lgkmcnt(3)
	v_mfma_f32_32x32x16_bf16 v[80:95], v[10:13], v[148:151], v[80:95]
	ds_read_b128 v[6:9], v223 offset:57344
	v_cvt_pk_bf16_f32 v240, v244, v245
	v_exp_f32_e32 v247, v247
	v_add_f32_e32 v0, v246, v0
	v_exp_f32_e32 v248, v248
	s_waitcnt lgkmcnt(3)
	v_mfma_f32_32x32x16_bf16 v[64:79], v[218:221], v[236:239], v[64:79]
	v_xor_b32_e32 v225, 0xe0, v15
	ds_read_b128 v[10:13], v225 offset:32768
	v_add_f32_e32 v0, v247, v0
	v_cvt_pk_bf16_f32 v241, v246, v247
	v_exp_f32_e32 v249, v249
	v_add_f32_e32 v0, v248, v0
	s_waitcnt lgkmcnt(3)
	v_mfma_f32_32x32x16_bf16 v[48:63], v[226:229], v[236:239], v[48:63]
	ds_read_b128 v[218:221], v225 offset:40960
	v_exp_f32_e32 v250, v250
	v_add_f32_e32 v0, v249, v0
	v_cvt_pk_bf16_f32 v242, v248, v249
	v_exp_f32_e32 v251, v251
	s_waitcnt lgkmcnt(3)
	v_mfma_f32_32x32x16_bf16 v[32:47], v[2:5], v[236:239], v[32:47]
	ds_read_b128 v[226:229], v225 offset:49152
	v_add_f32_e32 v0, v250, v0
	v_add_f32_e32 v0, v251, v0
	v_cvt_pk_bf16_f32 v243, v250, v251
	v_add_f32_e32 v196, v196, v0
	s_waitcnt lgkmcnt(3)
	v_mfma_f32_32x32x16_bf16 v[16:31], v[6:9], v[236:239], v[16:31]
	ds_read_b128 v[2:5], v225 offset:57344
	s_waitcnt lgkmcnt(3)
	v_mfma_f32_32x32x16_bf16 v[64:79], v[10:13], v[240:243], v[64:79]
	s_waitcnt lgkmcnt(2)
	v_mfma_f32_32x32x16_bf16 v[48:63], v[218:221], v[240:243], v[48:63]
	s_waitcnt lgkmcnt(1)
	v_mfma_f32_32x32x16_bf16 v[32:47], v[226:229], v[240:243], v[32:47]
	s_waitcnt lgkmcnt(0)
	v_mfma_f32_32x32x16_bf16 v[16:31], v[2:5], v[240:243], v[16:31]

.LBB0_423:
	s_add_i32 s1, s35, 0xffffff81
	s_cmp_gt_u32 s1, s34
	s_cbranch_scc1 .LBB0_420
	s_cmp_gt_u32 s35, s31
	s_cbranch_scc0 .Ldiff_fast0
	v_xor_b32_e32 v217, 32, v216
	v_xor_b32_e32 v218, 64, v216
	v_xor_b32_e32 v219, 0x60, v216
	v_xor_b32_e32 v220, 0x80, v216
	v_xor_b32_e32 v221, 0xa0, v216
	v_xor_b32_e32 v222, 0xc0, v216
	v_xor_b32_e32 v223, 0xe0, v216
	v_xor_b32_e32 v225, 32, v224
	v_xor_b32_e32 v226, 64, v224
	v_xor_b32_e32 v227, 0x60, v224
	v_xor_b32_e32 v228, 0x80, v224
	v_xor_b32_e32 v229, 0xa0, v224
	v_xor_b32_e32 v230, 0xc0, v224
	v_xor_b32_e32 v231, 0xe0, v224
	v_add_u32_e32 v235, -16, v193
	v_subrev_u32_e32 v236, 17, v193
	v_subrev_u32_e32 v237, 18, v193
	v_subrev_u32_e32 v238, 19, v193
	v_subrev_u32_e32 v239, 20, v193
	v_subrev_u32_e32 v240, 21, v193
	v_subrev_u32_e32 v241, 22, v193
	v_subrev_u32_e32 v242, 23, v193
	s_lshl_b32 s0, s0, 16
	s_add_i32 s0, s0, 0
	v_add_u32_e32 v10, s0, v215
	v_add_u32_e32 v245, v10, v216
	ds_read_b128 v[2:5], v245
	v_add_u32_e32 v244, v10, v217
	v_add_u32_e32 v243, v10, v218
	v_add_u32_e32 v15, v10, v219
	v_add_u32_e32 v248, v10, v221
	v_add_u32_e32 v14, s35, v194
	s_cmp_gt_u32 s35, s31
	v_add_u32_e32 v6, 0xffffff81, v14
	s_cselect_b64 vcc, -1, 0
	s_waitcnt lgkmcnt(0)
	v_mfma_f32_32x32x16_bf16 v[144:159], v[2:5], v[160:163], 0
	ds_read_b128 v[2:5], v244
	v_add_u32_e32 v0, s0, v195
	v_cmp_gt_i32_e64 s[0:1], v6, v193
	s_and_b64 s[84:85], vcc, s[0:1]
	v_cmp_lt_i32_e64 s[0:1], v6, v193
	v_add_u32_e32 v7, 0xffffff83, v14
	v_cmp_gt_i32_e64 s[4:5], v7, v193
	v_add_u32_e32 v8, 0xffffff84, v14
	s_waitcnt lgkmcnt(0)
	v_mfma_f32_32x32x16_bf16 v[144:159], v[2:5], v[164:167], v[144:159]
	ds_read_b128 v[2:5], v243
	s_and_b64 s[86:87], vcc, s[4:5]
	v_cmp_gt_i32_e64 s[4:5], v8, v193
	v_add_u32_e32 v9, 0xffffff85, v14
	s_and_b64 s[88:89], vcc, s[4:5]
	v_cmp_gt_i32_e64 s[4:5], v9, v193
	v_add_u32_e32 v11, 0xffffff86, v14
	s_waitcnt lgkmcnt(0)
	v_mfma_f32_32x32x16_bf16 v[144:159], v[2:5], v[168:171], v[144:159]
	ds_read_b128 v[2:5], v15
	ds_read_b128 v[250:253], v248
	s_and_b64 s[90:91], vcc, s[4:5]
	v_cmp_gt_i32_e64 s[4:5], v11, v193
	v_add_u32_e32 v12, 0xffffff87, v14
	s_and_b64 s[76:77], vcc, s[4:5]
	v_cmp_gt_i32_e64 s[4:5], v12, v193
	s_waitcnt lgkmcnt(0)
	v_mfma_f32_32x32x16_bf16 v[144:159], v[2:5], v[172:175], v[144:159]
	v_add_u32_e32 v13, 0xffffff88, v14
	s_and_b64 s[10:11], vcc, s[4:5]
	v_cmp_gt_i32_e64 s[4:5], v13, v193
	s_and_b64 s[46:47], vcc, s[4:5]
	v_cmp_gt_i32_e64 s[4:5], v6, v235
	s_and_b64 s[92:93], vcc, s[4:5]
	v_cmp_gt_i32_e64 s[4:5], v6, v236
	s_nop 4
	v_exp_f32_e32 v4, v145
	v_exp_f32_e32 v2, v144
	v_exp_f32_e32 v7, v147
	v_exp_f32_e32 v8, v148
	v_cndmask_b32_e64 v5, 0, v4, s[0:1]
	v_cndmask_b32_e32 v4, v4, v5, vcc
	v_exp_f32_e32 v5, v146
	v_cndmask_b32_e64 v2, v2, 0, s[84:85]
	v_add_f32_e32 v3, 0, v2
	v_exp_f32_e32 v9, v149
	v_add_f32_e32 v3, v3, v4
	v_cndmask_b32_e64 v5, v5, 0, s[86:87]
	v_exp_f32_e32 v11, v150
	v_add_f32_e32 v3, v5, v3
	v_cndmask_b32_e64 v7, v7, 0, s[88:89]
	v_exp_f32_e32 v12, v151
	v_add_f32_e32 v3, v7, v3
	v_cndmask_b32_e64 v8, v8, 0, s[90:91]
	v_exp_f32_e32 v13, v152
	v_add_f32_e32 v3, v8, v3
	v_cndmask_b32_e64 v9, v9, 0, s[76:77]
	v_exp_f32_e32 v144, v153
	v_add_f32_e32 v3, v9, v3
	v_cndmask_b32_e64 v11, v11, 0, s[10:11]
	v_exp_f32_e32 v145, v154
	v_add_f32_e32 v3, v11, v3
	v_cndmask_b32_e64 v12, v12, 0, s[46:47]
	v_exp_f32_e32 v146, v155
	v_add_f32_e32 v3, v12, v3
	v_cndmask_b32_e64 v13, v13, 0, s[92:93]
	s_and_b64 s[94:95], vcc, s[4:5]
	v_cmp_gt_i32_e64 s[4:5], v6, v237
	v_exp_f32_e32 v147, v156
	v_add_f32_e32 v3, v13, v3
	v_cndmask_b32_e64 v144, v144, 0, s[94:95]
	s_and_b64 s[20:21], vcc, s[4:5]
	v_cmp_gt_i32_e64 s[4:5], v6, v238
	v_exp_f32_e32 v148, v157
	v_add_f32_e32 v3, v144, v3
	v_cndmask_b32_e64 v145, v145, 0, s[20:21]
	s_and_b64 s[96:97], vcc, s[4:5]
	v_cmp_gt_i32_e64 s[4:5], v6, v239
	v_exp_f32_e32 v149, v158
	v_add_f32_e32 v3, v145, v3
	v_cndmask_b32_e64 v146, v146, 0, s[96:97]
	s_and_b64 s[50:51], vcc, s[4:5]
	v_cmp_gt_i32_e64 s[4:5], v6, v240
	v_exp_f32_e32 v150, v159
	v_add_f32_e32 v3, v146, v3
	v_cndmask_b32_e64 v147, v147, 0, s[50:51]
	s_and_b64 s[48:49], vcc, s[4:5]
	v_cmp_gt_i32_e64 s[4:5], v6, v241
	v_add_f32_e32 v3, v147, v3
	v_cndmask_b32_e64 v148, v148, 0, s[48:49]
	s_and_b64 s[6:7], vcc, s[4:5]
	v_cmp_gt_i32_e64 s[4:5], v6, v242
	v_add_f32_e32 v3, v148, v3
	v_cndmask_b32_e64 v149, v149, 0, s[6:7]
	s_and_b64 s[4:5], vcc, s[4:5]
	v_add_f32_e32 v3, v149, v3
	v_cndmask_b32_e64 v150, v150, 0, s[4:5]
	v_add_f32_e32 v3, v150, v3
	v_add_u32_e32 v249, v10, v220
	v_add_f32_e32 v197, v197, v3
	v_cvt_pk_bf16_f32 v6, v2, v4
	v_cvt_pk_bf16_f32 v2, v13, v144
	v_cvt_pk_bf16_f32 v3, v145, v146
	v_cvt_pk_bf16_f32 v4, v147, v148
	ds_read_b128 v[144:147], v249
	v_cvt_pk_bf16_f32 v7, v5, v7
	v_cvt_pk_bf16_f32 v5, v149, v150
	s_waitcnt lgkmcnt(0)
	v_mfma_f32_32x32x16_bf16 v[144:159], v[144:147], v[176:179], 0
	v_add_u32_e32 v247, v10, v222
	v_add_u32_e32 v246, v10, v223
	v_cvt_pk_bf16_f32 v8, v8, v9
	v_cvt_pk_bf16_f32 v9, v11, v12
	ds_read_b128 v[10:13], v246
	v_mfma_f32_32x32x16_bf16 v[144:159], v[250:253], v[180:183], v[144:159]
	ds_read_b128 v[250:253], v247
	s_waitcnt lgkmcnt(0)
	v_mfma_f32_32x32x16_bf16 v[144:159], v[250:253], v[184:187], v[144:159]
	v_mfma_f32_32x32x16_bf16 v[144:159], v[10:13], v[188:191], v[144:159]
	s_nop 11
	v_exp_f32_e32 v10, v144
	v_exp_f32_e32 v144, v147
	v_exp_f32_e32 v12, v145
	v_cndmask_b32_e64 v10, v10, 0, s[84:85]
	v_cndmask_b32_e64 v145, v144, 0, s[88:89]
	v_exp_f32_e32 v144, v148
	v_cndmask_b32_e64 v13, 0, v12, s[0:1]
	v_cndmask_b32_e32 v12, v12, v13, vcc
	v_exp_f32_e32 v13, v146
	v_cndmask_b32_e64 v146, v144, 0, s[90:91]
	v_exp_f32_e32 v144, v149
	v_add_f32_e32 v11, 0, v10
	v_add_f32_e32 v11, v11, v12
	v_cndmask_b32_e64 v13, v13, 0, s[86:87]
	v_cndmask_b32_e64 v147, v144, 0, s[76:77]
	v_exp_f32_e32 v144, v150
	v_add_f32_e32 v11, v13, v11
	v_add_f32_e32 v11, v145, v11
	v_add_f32_e32 v11, v146, v11
	v_cndmask_b32_e64 v148, v144, 0, s[10:11]
	v_exp_f32_e32 v144, v151
	v_add_f32_e32 v11, v147, v11
	v_add_f32_e32 v11, v148, v11
	v_cvt_pk_bf16_f32 v146, v146, v147
	v_cndmask_b32_e64 v149, v144, 0, s[46:47]
	v_exp_f32_e32 v144, v152
	v_add_f32_e32 v11, v149, v11
	v_cvt_pk_bf16_f32 v147, v148, v149
	v_cvt_pk_bf16_f32 v145, v13, v145
	v_cndmask_b32_e64 v150, v144, 0, s[92:93]
	v_exp_f32_e32 v144, v153
	v_add_f32_e32 v11, v150, v11
	s_add_i32 s0, s35, 0xffffffa1
	s_cmp_gt_u32 s0, s34
	v_cndmask_b32_e64 v151, v144, 0, s[94:95]
	v_exp_f32_e32 v144, v154
	v_add_f32_e32 v11, v151, v11
	v_cndmask_b32_e64 v152, v144, 0, s[20:21]
	v_exp_f32_e32 v144, v155
	v_add_f32_e32 v11, v152, v11
	v_cndmask_b32_e64 v153, v144, 0, s[96:97]
	v_exp_f32_e32 v144, v156
	v_add_f32_e32 v11, v153, v11
	v_cndmask_b32_e64 v154, v144, 0, s[50:51]
	v_exp_f32_e32 v144, v157
	v_add_f32_e32 v11, v154, v11
	v_cndmask_b32_e64 v155, v144, 0, s[48:49]
	v_exp_f32_e32 v144, v158
	v_add_f32_e32 v11, v155, v11
	v_cndmask_b32_e64 v156, v144, 0, s[6:7]
	v_exp_f32_e32 v144, v159
	v_add_f32_e32 v11, v156, v11
	v_cndmask_b32_e64 v157, v144, 0, s[4:5]
	v_add_f32_e32 v158, v157, v11
	v_cvt_pk_bf16_f32 v11, v152, v153
	v_add_u32_e32 v152, v0, v224
	v_cvt_pk_bf16_f32 v144, v10, v12
	v_cvt_pk_bf16_f32 v10, v150, v151
	ds_read_b128 v[148:151], v152 offset:32768
	v_add_u32_e32 v153, v0, v225
	s_waitcnt lgkmcnt(0)
	v_mfma_f32_32x32x16_bf16 v[128:143], v[148:151], v[6:9], v[128:143]
	v_cvt_pk_bf16_f32 v12, v154, v155
	v_cvt_pk_bf16_f32 v13, v156, v157
	v_add_f32_e32 v196, v196, v158
	v_mfma_f32_32x32x16_bf16 v[64:79], v[148:151], v[144:147], v[64:79]
	ds_read_b128 v[148:151], v153 offset:32768
	s_waitcnt lgkmcnt(0)
	v_mfma_f32_32x32x16_bf16 v[128:143], v[148:151], v[2:5], v[128:143]
	v_mfma_f32_32x32x16_bf16 v[64:79], v[148:151], v[10:13], v[64:79]
	ds_read_b128 v[148:151], v152 offset:40960
	s_waitcnt lgkmcnt(0)
	v_mfma_f32_32x32x16_bf16 v[112:127], v[148:151], v[6:9], v[112:127]
	v_mfma_f32_32x32x16_bf16 v[48:63], v[148:151], v[144:147], v[48:63]
	ds_read_b128 v[148:151], v153 offset:40960
	s_waitcnt lgkmcnt(0)
	v_mfma_f32_32x32x16_bf16 v[112:127], v[148:151], v[2:5], v[112:127]
	v_mfma_f32_32x32x16_bf16 v[48:63], v[148:151], v[10:13], v[48:63]
	ds_read_b128 v[148:151], v152 offset:49152
	s_waitcnt lgkmcnt(0)
	v_mfma_f32_32x32x16_bf16 v[96:111], v[148:151], v[6:9], v[96:111]
	v_mfma_f32_32x32x16_bf16 v[32:47], v[148:151], v[144:147], v[32:47]
	ds_read_b128 v[148:151], v153 offset:49152
	s_waitcnt lgkmcnt(0)
	v_mfma_f32_32x32x16_bf16 v[96:111], v[148:151], v[2:5], v[96:111]
	v_mfma_f32_32x32x16_bf16 v[32:47], v[148:151], v[10:13], v[32:47]
	ds_read_b128 v[148:151], v152 offset:57344
	s_waitcnt lgkmcnt(0)
	v_mfma_f32_32x32x16_bf16 v[80:95], v[148:151], v[6:9], v[80:95]
	ds_read_b128 v[6:9], v153 offset:57344
	v_mfma_f32_32x32x16_bf16 v[16:31], v[148:151], v[144:147], v[16:31]
	s_waitcnt lgkmcnt(0)
	v_mfma_f32_32x32x16_bf16 v[80:95], v[6:9], v[2:5], v[80:95]
	v_mfma_f32_32x32x16_bf16 v[16:31], v[6:9], v[10:13], v[16:31]
	s_cbranch_scc1 .LBB0_427
	ds_read_b128 v[2:5], v245 offset:8192
	v_add_u32_e32 v6, 0xffffffa1, v14
	v_cmp_gt_i32_e64 s[0:1], v6, v193
	s_and_b64 s[84:85], vcc, s[0:1]
	v_cmp_lt_i32_e64 s[0:1], v6, v193
	v_add_u32_e32 v7, 0xffffffa3, v14
	v_cmp_gt_i32_e64 s[4:5], v7, v193
	v_add_u32_e32 v8, 0xffffffa4, v14
	s_and_b64 s[86:87], vcc, s[4:5]
	s_waitcnt lgkmcnt(0)
	v_mfma_f32_32x32x16_bf16 v[144:159], v[2:5], v[160:163], 0
	ds_read_b128 v[2:5], v244 offset:8192
	v_cmp_gt_i32_e64 s[4:5], v8, v193
	v_add_u32_e32 v9, 0xffffffa5, v14
	s_and_b64 s[88:89], vcc, s[4:5]
	v_cmp_gt_i32_e64 s[4:5], v9, v193
	v_add_u32_e32 v10, 0xffffffa6, v14
	s_and_b64 s[90:91], vcc, s[4:5]
	v_cmp_gt_i32_e64 s[4:5], v10, v193
	s_waitcnt lgkmcnt(0)
	v_mfma_f32_32x32x16_bf16 v[144:159], v[2:5], v[164:167], v[144:159]
	ds_read_b128 v[2:5], v243 offset:8192
	v_add_u32_e32 v11, 0xffffffa7, v14
	s_and_b64 s[92:93], vcc, s[4:5]
	v_cmp_gt_i32_e64 s[4:5], v11, v193
	v_add_u32_e32 v12, 0xffffffa8, v14
	s_and_b64 s[94:95], vcc, s[4:5]
	v_cmp_gt_i32_e64 s[4:5], v12, v193
	s_waitcnt lgkmcnt(0)
	v_mfma_f32_32x32x16_bf16 v[144:159], v[2:5], v[168:171], v[144:159]
	ds_read_b128 v[2:5], v15 offset:8192
	s_and_b64 s[76:77], vcc, s[4:5]
	v_cmp_gt_i32_e64 s[4:5], v6, v235
	s_and_b64 s[6:7], vcc, s[4:5]
	v_cmp_gt_i32_e64 s[4:5], v6, v236
	s_and_b64 s[10:11], vcc, s[4:5]
	v_cmp_gt_i32_e64 s[4:5], v6, v237
	s_waitcnt lgkmcnt(0)
	v_mfma_f32_32x32x16_bf16 v[144:159], v[2:5], v[172:175], v[144:159]
	s_and_b64 s[46:47], vcc, s[4:5]
	v_cmp_gt_i32_e64 s[4:5], v6, v238
	s_and_b64 s[48:49], vcc, s[4:5]
	v_cmp_gt_i32_e64 s[4:5], v6, v239
	s_and_b64 s[50:51], vcc, s[4:5]
	v_cmp_gt_i32_e64 s[4:5], v6, v240
	s_and_b64 s[20:21], vcc, s[4:5]
	s_nop 4
	v_exp_f32_e32 v4, v145
	v_exp_f32_e32 v2, v144
	v_exp_f32_e32 v7, v147
	v_exp_f32_e32 v8, v148
	v_cndmask_b32_e64 v5, 0, v4, s[0:1]
	v_cndmask_b32_e32 v4, v4, v5, vcc
	v_exp_f32_e32 v5, v146
	v_cndmask_b32_e64 v2, v2, 0, s[84:85]
	v_add_f32_e32 v3, 0, v2
	v_exp_f32_e32 v9, v149
	v_add_f32_e32 v3, v3, v4
	v_cndmask_b32_e64 v5, v5, 0, s[86:87]
	v_exp_f32_e32 v10, v150
	v_add_f32_e32 v3, v5, v3
	v_cndmask_b32_e64 v7, v7, 0, s[88:89]
	v_exp_f32_e32 v11, v151
	v_add_f32_e32 v3, v7, v3
	v_cndmask_b32_e64 v8, v8, 0, s[90:91]
	v_exp_f32_e32 v12, v152
	v_add_f32_e32 v3, v8, v3
	v_cndmask_b32_e64 v9, v9, 0, s[92:93]
	v_exp_f32_e32 v13, v153
	v_add_f32_e32 v3, v9, v3
	v_cndmask_b32_e64 v10, v10, 0, s[94:95]
	v_add_f32_e32 v3, v10, v3
	v_cndmask_b32_e64 v11, v11, 0, s[76:77]
	v_add_f32_e32 v3, v11, v3
	v_cndmask_b32_e64 v12, v12, 0, s[6:7]
	v_exp_f32_e32 v144, v154
	v_add_f32_e32 v3, v12, v3
	v_cndmask_b32_e64 v13, v13, 0, s[10:11]
	v_exp_f32_e32 v145, v155
	v_cmp_gt_i32_e64 s[4:5], v6, v241
	v_add_f32_e32 v3, v13, v3
	v_exp_f32_e32 v146, v156
	s_and_b64 s[96:97], vcc, s[4:5]
	v_cmp_gt_i32_e64 s[4:5], v6, v242
	v_cvt_pk_bf16_f32 v6, v2, v4
	v_cvt_pk_bf16_f32 v8, v8, v9
	v_cvt_pk_bf16_f32 v9, v10, v11
	v_cvt_pk_bf16_f32 v2, v12, v13
	ds_read_b128 v[10:13], v249 offset:8192
	v_exp_f32_e32 v147, v157
	v_cndmask_b32_e64 v144, v144, 0, s[46:47]
	v_exp_f32_e32 v148, v158
	v_add_f32_e32 v3, v144, v3
	v_cndmask_b32_e64 v145, v145, 0, s[48:49]
	v_exp_f32_e32 v149, v159
	v_add_f32_e32 v3, v145, v3
	v_cndmask_b32_e64 v146, v146, 0, s[50:51]
	v_add_f32_e32 v3, v146, v3
	v_cndmask_b32_e64 v147, v147, 0, s[20:21]
	v_add_f32_e32 v3, v147, v3
	v_cndmask_b32_e64 v148, v148, 0, s[96:97]
	s_and_b64 s[4:5], vcc, s[4:5]
	v_add_f32_e32 v3, v148, v3
	v_cndmask_b32_e64 v149, v149, 0, s[4:5]
	v_add_f32_e32 v3, v149, v3
	v_add_f32_e32 v197, v197, v3
	v_cvt_pk_bf16_f32 v7, v5, v7
	v_cvt_pk_bf16_f32 v3, v144, v145
	v_cvt_pk_bf16_f32 v4, v146, v147
	v_cvt_pk_bf16_f32 v5, v148, v149
	s_waitcnt lgkmcnt(0)
	v_mfma_f32_32x32x16_bf16 v[144:159], v[10:13], v[176:179], 0
	ds_read_b128 v[10:13], v248 offset:8192
	s_waitcnt lgkmcnt(0)
	v_mfma_f32_32x32x16_bf16 v[144:159], v[10:13], v[180:183], v[144:159]
	ds_read_b128 v[10:13], v247 offset:8192
	s_waitcnt lgkmcnt(0)
	v_mfma_f32_32x32x16_bf16 v[144:159], v[10:13], v[184:187], v[144:159]
	ds_read_b128 v[10:13], v246 offset:8192
	s_waitcnt lgkmcnt(0)
	v_mfma_f32_32x32x16_bf16 v[144:159], v[10:13], v[188:191], v[144:159]
	s_nop 11
	v_exp_f32_e32 v10, v144
	v_exp_f32_e32 v144, v147
	v_exp_f32_e32 v12, v145
	v_cndmask_b32_e64 v10, v10, 0, s[84:85]
	v_cndmask_b32_e64 v145, v144, 0, s[88:89]
	v_exp_f32_e32 v144, v148
	v_cndmask_b32_e64 v13, 0, v12, s[0:1]
	v_cndmask_b32_e32 v12, v12, v13, vcc
	v_exp_f32_e32 v13, v146
	v_cndmask_b32_e64 v146, v144, 0, s[90:91]
	v_exp_f32_e32 v144, v149
	v_add_f32_e32 v11, 0, v10
	v_add_f32_e32 v11, v11, v12
	v_cndmask_b32_e64 v13, v13, 0, s[86:87]
	v_cndmask_b32_e64 v147, v144, 0, s[92:93]
	v_exp_f32_e32 v144, v150
	v_add_f32_e32 v11, v13, v11
	v_add_f32_e32 v11, v145, v11
	v_add_f32_e32 v11, v146, v11
	v_cndmask_b32_e64 v148, v144, 0, s[94:95]
	v_exp_f32_e32 v144, v151
	v_add_f32_e32 v11, v147, v11
	v_add_f32_e32 v11, v148, v11
	v_cvt_pk_bf16_f32 v146, v146, v147
	v_cndmask_b32_e64 v149, v144, 0, s[76:77]
	v_exp_f32_e32 v144, v152
	v_add_f32_e32 v11, v149, v11
	v_cvt_pk_bf16_f32 v147, v148, v149
	v_cvt_pk_bf16_f32 v145, v13, v145
	v_cndmask_b32_e64 v150, v144, 0, s[6:7]
	v_exp_f32_e32 v144, v153
	v_add_f32_e32 v11, v150, v11
	v_cndmask_b32_e64 v151, v144, 0, s[10:11]
	v_exp_f32_e32 v144, v154
	v_add_f32_e32 v11, v151, v11
	v_cndmask_b32_e64 v152, v144, 0, s[46:47]
	v_exp_f32_e32 v144, v155
	v_add_f32_e32 v11, v152, v11
	v_cndmask_b32_e64 v153, v144, 0, s[48:49]
	v_exp_f32_e32 v144, v156
	v_add_f32_e32 v11, v153, v11
	v_cndmask_b32_e64 v154, v144, 0, s[50:51]
	v_exp_f32_e32 v144, v157
	v_add_f32_e32 v11, v154, v11
	v_cndmask_b32_e64 v155, v144, 0, s[20:21]
	v_exp_f32_e32 v144, v158
	v_add_f32_e32 v11, v155, v11
	v_cndmask_b32_e64 v156, v144, 0, s[96:97]
	v_exp_f32_e32 v144, v159
	v_add_f32_e32 v11, v156, v11
	v_cndmask_b32_e64 v157, v144, 0, s[4:5]
	v_add_f32_e32 v158, v157, v11
	v_cvt_pk_bf16_f32 v11, v152, v153
	v_add_u32_e32 v152, v0, v226
	v_cvt_pk_bf16_f32 v144, v10, v12
	v_cvt_pk_bf16_f32 v10, v150, v151
	ds_read_b128 v[148:151], v152 offset:32768
	v_add_u32_e32 v153, v0, v227
	s_waitcnt lgkmcnt(0)
	v_mfma_f32_32x32x16_bf16 v[128:143], v[148:151], v[6:9], v[128:143]
	v_cvt_pk_bf16_f32 v12, v154, v155
	v_cvt_pk_bf16_f32 v13, v156, v157
	v_add_f32_e32 v196, v196, v158
	v_mfma_f32_32x32x16_bf16 v[64:79], v[148:151], v[144:147], v[64:79]
	ds_read_b128 v[148:151], v153 offset:32768
	s_waitcnt lgkmcnt(0)
	v_mfma_f32_32x32x16_bf16 v[128:143], v[148:151], v[2:5], v[128:143]
	v_mfma_f32_32x32x16_bf16 v[64:79], v[148:151], v[10:13], v[64:79]
	ds_read_b128 v[148:151], v152 offset:40960
	s_waitcnt lgkmcnt(0)
	v_mfma_f32_32x32x16_bf16 v[112:127], v[148:151], v[6:9], v[112:127]
	v_mfma_f32_32x32x16_bf16 v[48:63], v[148:151], v[144:147], v[48:63]
	ds_read_b128 v[148:151], v153 offset:40960
	s_waitcnt lgkmcnt(0)
	v_mfma_f32_32x32x16_bf16 v[112:127], v[148:151], v[2:5], v[112:127]
	v_mfma_f32_32x32x16_bf16 v[48:63], v[148:151], v[10:13], v[48:63]
	ds_read_b128 v[148:151], v152 offset:49152
	s_waitcnt lgkmcnt(0)
	v_mfma_f32_32x32x16_bf16 v[96:111], v[148:151], v[6:9], v[96:111]
	v_mfma_f32_32x32x16_bf16 v[32:47], v[148:151], v[144:147], v[32:47]
	ds_read_b128 v[148:151], v153 offset:49152
	s_waitcnt lgkmcnt(0)
	v_mfma_f32_32x32x16_bf16 v[96:111], v[148:151], v[2:5], v[96:111]
	v_mfma_f32_32x32x16_bf16 v[32:47], v[148:151], v[10:13], v[32:47]
	ds_read_b128 v[148:151], v152 offset:57344
	s_waitcnt lgkmcnt(0)
	v_mfma_f32_32x32x16_bf16 v[80:95], v[148:151], v[6:9], v[80:95]
	ds_read_b128 v[6:9], v153 offset:57344
	v_mfma_f32_32x32x16_bf16 v[16:31], v[148:151], v[144:147], v[16:31]
	s_waitcnt lgkmcnt(0)
	v_mfma_f32_32x32x16_bf16 v[80:95], v[6:9], v[2:5], v[80:95]
	v_mfma_f32_32x32x16_bf16 v[16:31], v[6:9], v[10:13], v[16:31]
	s_sub_i32 s0, s35, 63
	s_cmp_gt_u32 s0, s34
	s_cbranch_scc0 .LBB0_428
